# v52: v45 + HGRN unit reloads of early-consumed scalars issued right after their last reader inside the gating section (index clamped, no skip branch, exit drain)
# speedup vs baseline: 1.0071x; 1.0071x over previous
; #define LAS __attribute__((address_space(3)))
; __device__ __forceinline__ int opaque_tid() { int t = threadIdx.x; asm volatile("" : "+v"(t)); return t; }
; #define HM_LOAD(RQ, RZ, RV, j_) do { _Pragma("unroll") for (int i = 0; i < 16; ++i) { const bf16_t* pr_ = proj + HM_TOK((j_) * 16 + i) * INW; RQ[i] = pr_[qc]; RZ[i] = pr_[zc]; RV[i] = pr_[vc]; } } while (0)
; __device__ __forceinline__ void hgrn_mfma_unit(const Params& P, int l, LAS unsigned char* lds, int b, int half) {
;     const int tid = opaque_tid(), lane = tid & 63, wave = tid >> 6, c16 = lane & 15, g = lane >> 4;
;     if (wave < 4) {
;         const int idx = 4 * half + wave, h = idx >> 1, dir = idx & 1;
;         const bf16_t* proj = (const bf16_t*)(P.ws + WS_PROJ);
;         float* odir = (float*)(P.ws + WS_ODIR) + (size_t)dir * ROWS * 256;
;         LAS unsigned char* wl = lds + wave * HM_WAVE;
;         const float lb = ((const float*)(P.ws + WS_CTL))[CW_LB + ((size_t)dir * DEPTH + l) * 256 + h * 64 + lane];
;         const float oml = 1.0f - lb;
;         const int qc = PB_Q + h * 64 + lane, zc = (dir ? PB_FB : PB_FF) + h * 64 + lane, vc = PB_I + h * 64 + lane;
;         const size_t tb = (size_t)b * TT;
;     ...
;         unsigned aq[16], az[16], av[16], bq[16], bz[16], bv[16];
;         HM_LOAD(aq, az, av, 0); HM_LOAD(bq, bz, bv, 1);
.LBB0_461:
	s_andn2_b64 vcc, exec, s[10:11]
	s_cbranch_vccnz .LBB0_719
	v_mov_b32_e32 v8, v200
	v_mov_b32_e32 v202, 0x358637bd
	v_ashrrev_i32_e32 v0, 6, v8
	v_mov_b32_e32 v201, 1
	v_mov_b32_e32 v203, 0x400
	v_cmp_gt_i32_e32 vcc, 4, v0
	s_and_saveexec_b64 s[10:11], vcc
	s_cbranch_execz .LBB0_718
	v_and_b32_e32 v5, 1, v0
	s_mov_b32 s9, 0x2400000
	v_mul_lo_u32 v128, v5, s9
	s_movk_i32 s9, 0x2300
	v_mul_lo_u32 v11, v0, s9
	s_lshl_b32 s9, s37, 7
	s_and_b32 s9, s9, 0x80
	v_bfe_i32 v4, v0, 0, 1
	v_lshl_add_u32 v0, v0, 5, s9
	v_and_b32_e32 v130, 0xffffffc0, v0
	v_readlane_b32 s18, v255, 24
	v_ashrrev_i32_e32 v131, 31, v130
	v_lshlrev_b32_e32 v0, 12, v5
	v_mov_b32_e32 v1, v129
	v_readlane_b32 s19, v255, 25
	v_and_b32_e32 v9, 63, v8
	v_lshlrev_b32_e32 v132, 2, v9
	v_lshl_add_u64 v[2:3], s[18:19], 0, v[0:1]
	v_lshlrev_b64 v[0:1], 2, v[130:131]
	v_lshl_add_u64 v[2:3], v[2:3], 0, v[0:1]
	v_mov_b32_e32 v133, v129
	v_lshl_add_u64 v[2:3], v[2:3], 0, v[132:133]
	s_movk_i32 s13, 0x2000
	v_add_co_u32_e32 v6, vcc, s13, v2
	s_add_i32 s8, s37, 0xffffff80
	s_nop 0
	v_addc_co_u32_e32 v7, vcc, 0, v3, vcc
	v_cmp_eq_u32_e32 vcc, 0, v5
	v_mov_b32_e32 v2, 0x500
	s_lshr_b32 s12, s8, 1
	v_cndmask_b32_e32 v2, v2, v203, vcc
	v_mov_b32_e32 v16, 0xfe
	v_bfrev_b32_e32 v20, -0.5
	v_add_u32_e32 v2, v2, v130
	s_mul_i32 s64, s12, 0x900
	v_cndmask_b32_e64 v16, v16, 1, vcc
	v_cndmask_b32_e64 v20, v20, 2, vcc
	v_or_b32_e32 v134, v2, v9
	v_or_b32_sdwa v2, v4, s64 dst_sel:DWORD dst_unused:UNUSED_PAD src0_sel:BYTE_0 src1_sel:DWORD
	s_movk_i32 s12, 0xb00
	v_or_b32_e32 v16, s64, v16
	v_or_b32_e32 v20, s64, v20
	v_ashrrev_i32_e32 v135, 31, v134
	v_mul_lo_u32 v2, v2, s12
	v_mov_b32_e32 v3, v129
	v_or_b32_e32 v130, v130, v9
	v_mul_lo_u32 v16, v16, s12
	v_mov_b32_e32 v17, v129
	v_mul_lo_u32 v20, v20, s12
	v_mov_b32_e32 v21, v129
	v_cmp_eq_u32_e64 s[38:39], 1, v5
	v_lshl_add_u64 v[12:13], v[2:3], 1, s[56:57]
	v_lshlrev_b64 v[4:5], 1, v[130:131]
	v_lshlrev_b64 v[2:3], 1, v[134:135]
	v_lshlrev_b32_e32 v130, 1, v130
	v_lshlrev_b32_e32 v134, 1, v134
	v_lshl_add_u64 v[16:17], v[16:17], 1, s[56:57]
	v_lshl_add_u64 v[20:21], v[20:21], 1, s[56:57]
	v_lshl_add_u64 v[14:15], v[12:13], 0, v[4:5]
	v_lshl_add_u64 v[12:13], v[12:13], 0, v[2:3]
	v_lshl_add_u64 v[18:19], v[16:17], 0, v[4:5]
	v_lshl_add_u64 v[16:17], v[16:17], 0, v[2:3]
	v_lshl_add_u64 v[22:23], v[20:21], 0, v[4:5]
	global_load_dword v24, v[6:7], off
	global_load_ushort v149, v[14:15], off offset:1536
	global_load_ushort v151, v[12:13], off
	global_load_ushort v148, v[18:19], off offset:1536
	global_load_ushort v150, v[16:17], off
	global_load_ushort v147, v[22:23], off offset:1536
	global_load_ushort v152, v[18:19], off offset:3072
	global_load_ushort v153, v[14:15], off offset:3072
	v_bfrev_b32_e32 v12, 0.5
	v_mov_b32_e32 v16, 0xfb
	v_cndmask_b32_e64 v12, v12, 3, vcc
	v_cndmask_b32_e64 v16, v16, 4, vcc
	v_or_b32_e32 v12, s64, v12
	v_or_b32_e32 v16, s64, v16
	v_mul_lo_u32 v12, v12, s12
	v_mov_b32_e32 v13, v129
	v_mul_lo_u32 v16, v16, s12
	v_mov_b32_e32 v17, v129
	v_lshl_add_u64 v[6:7], v[20:21], 0, v[2:3]
	v_lshl_add_u64 v[12:13], v[12:13], 1, s[56:57]
	v_lshl_add_u64 v[16:17], v[16:17], 1, s[56:57]
	v_lshl_add_u64 v[14:15], v[12:13], 0, v[4:5]
	v_lshl_add_u64 v[12:13], v[12:13], 0, v[2:3]
	v_lshl_add_u64 v[18:19], v[16:17], 0, v[4:5]
	v_lshl_add_u64 v[16:17], v[16:17], 0, v[2:3]
	global_load_ushort v158, v[6:7], off
	global_load_ushort v155, v[14:15], off offset:1536
	global_load_ushort v157, v[12:13], off
	global_load_ushort v154, v[18:19], off offset:1536
	global_load_ushort v156, v[16:17], off
	global_load_ushort v159, v[18:19], off offset:3072
	global_load_ushort v160, v[14:15], off offset:3072
	global_load_ushort v161, v[22:23], off offset:3072
	v_mov_b32_e32 v6, 0xfa
	v_cndmask_b32_e64 v6, v6, 5, vcc
	v_mov_b32_e32 v14, 0xf9
	v_mov_b32_e32 v18, 0xf8
	v_or_b32_e32 v6, s64, v6
	v_cndmask_b32_e64 v14, v14, 6, vcc
	v_cndmask_b32_e64 v18, v18, 7, vcc
	v_mul_lo_u32 v6, v6, s12
	v_mov_b32_e32 v7, v129
	v_or_b32_e32 v14, s64, v14
	v_or_b32_e32 v18, s64, v18
	v_lshl_add_u64 v[6:7], v[6:7], 1, s[56:57]
	v_mul_lo_u32 v14, v14, s12
	v_mov_b32_e32 v15, v129
	v_mul_lo_u32 v18, v18, s12
	v_mov_b32_e32 v19, v129
	v_lshl_add_u64 v[12:13], v[6:7], 0, v[4:5]
	v_lshl_add_u64 v[14:15], v[14:15], 1, s[56:57]
	v_lshl_add_u64 v[18:19], v[18:19], 1, s[56:57]
	v_lshl_add_u64 v[6:7], v[6:7], 0, v[2:3]
	v_lshl_add_u64 v[16:17], v[14:15], 0, v[4:5]
	v_lshl_add_u64 v[14:15], v[14:15], 0, v[2:3]
	v_lshl_add_u64 v[20:21], v[18:19], 0, v[4:5]
	global_load_ushort v164, v[12:13], off offset:1536
	global_load_ushort v166, v[6:7], off
	global_load_ushort v163, v[16:17], off offset:1536
	global_load_ushort v165, v[14:15], off
	global_load_ushort v162, v[20:21], off offset:1536
	global_load_ushort v167, v[20:21], off offset:3072
	global_load_ushort v168, v[16:17], off offset:3072
	global_load_ushort v169, v[12:13], off offset:3072
	v_mov_b32_e32 v12, 0xf7
	v_cndmask_b32_e64 v12, v12, 8, vcc
	v_mov_b32_e32 v16, 0xf6
	v_mov_b32_e32 v20, 0xf5
	v_or_b32_e32 v12, s64, v12
	v_cndmask_b32_e64 v16, v16, 9, vcc
	v_cndmask_b32_e64 v20, v20, 10, vcc
	v_mul_lo_u32 v12, v12, s12
	v_mov_b32_e32 v13, v129
	v_or_b32_e32 v16, s64, v16
	v_or_b32_e32 v20, s64, v20
	v_lshl_add_u64 v[12:13], v[12:13], 1, s[56:57]
	v_mul_lo_u32 v16, v16, s12
	v_mov_b32_e32 v17, v129
	v_mul_lo_u32 v20, v20, s12
	v_mov_b32_e32 v21, v129
	v_lshl_add_u64 v[6:7], v[18:19], 0, v[2:3]
	v_lshl_add_u64 v[14:15], v[12:13], 0, v[4:5]
	v_lshl_add_u64 v[12:13], v[12:13], 0, v[2:3]
	v_lshl_add_u64 v[16:17], v[16:17], 1, s[56:57]
	v_lshl_add_u64 v[20:21], v[20:21], 1, s[56:57]
	v_lshl_add_u64 v[18:19], v[16:17], 0, v[4:5]
; #define HM_LOAD(RQ, RZ, RV, j_) do { _Pragma("unroll") for (int i = 0; i < 16; ++i) { const bf16_t* pr_ = proj + HM_TOK((j_) * 16 + i) * INW; RQ[i] = pr_[qc]; RZ[i] = pr_[zc]; RV[i] = pr_[vc]; } } while (0)
; __device__ __forceinline__ void hgrn_mfma_unit(const Params& P, int l, LAS unsigned char* lds, int b, int half) {
;     ...
;         const float lb = ((const float*)(P.ws + WS_CTL))[CW_LB + ((size_t)dir * DEPTH + l) * 256 + h * 64 + lane];
;         const float oml = 1.0f - lb;
;         const int qc = PB_Q + h * 64 + lane, zc = (dir ? PB_FB : PB_FF) + h * 64 + lane, vc = PB_I + h * 64 + lane;
;         const size_t tb = (size_t)b * TT;
;     ...
;         unsigned aq[16], az[16], av[16], bq[16], bz[16], bv[16];
;         HM_LOAD(aq, az, av, 0); HM_LOAD(bq, bz, bv, 1);
	v_lshl_add_u64 v[16:17], v[16:17], 0, v[2:3]
	v_lshl_add_u64 v[22:23], v[20:21], 0, v[4:5]
	global_load_ushort v175, v[6:7], off
	global_load_ushort v172, v[14:15], off offset:1536
	global_load_ushort v174, v[12:13], off
	global_load_ushort v171, v[18:19], off offset:1536
	global_load_ushort v173, v[16:17], off
	global_load_ushort v170, v[22:23], off offset:1536
	global_load_ushort v176, v[18:19], off offset:3072
	global_load_ushort v177, v[14:15], off offset:3072
	v_mov_b32_e32 v12, 0xf4
	v_cndmask_b32_e64 v12, v12, 11, vcc
	v_mov_b32_e32 v16, 0xf3
	v_or_b32_e32 v12, s64, v12
	v_cndmask_b32_e64 v16, v16, 12, vcc
	v_mul_lo_u32 v12, v12, s12
	v_mov_b32_e32 v13, v129
	v_or_b32_e32 v16, s64, v16
	v_lshl_add_u64 v[12:13], v[12:13], 1, s[56:57]
	v_mul_lo_u32 v16, v16, s12
	v_mov_b32_e32 v17, v129
	v_lshl_add_u64 v[6:7], v[20:21], 0, v[2:3]
	v_lshl_add_u64 v[14:15], v[12:13], 0, v[4:5]
	v_lshl_add_u64 v[16:17], v[16:17], 1, s[56:57]
	v_lshl_add_u64 v[12:13], v[12:13], 0, v[2:3]
	v_lshl_add_u64 v[18:19], v[16:17], 0, v[4:5]
	v_lshl_add_u64 v[16:17], v[16:17], 0, v[2:3]
	global_load_ushort v190, v[6:7], off
	global_load_ushort v187, v[14:15], off offset:1536
	global_load_ushort v189, v[12:13], off
	global_load_ushort v186, v[18:19], off offset:1536
	global_load_ushort v188, v[16:17], off
	global_load_ushort v191, v[18:19], off offset:3072
	global_load_ushort v192, v[14:15], off offset:3072
	global_load_ushort v193, v[22:23], off offset:3072
	v_mov_b32_e32 v6, 0xf2
	v_mov_b32_e32 v14, 0xf1
	v_cndmask_b32_e64 v6, v6, 13, vcc
	v_cndmask_b32_e64 v14, v14, 14, vcc
	v_mov_b32_e32 v18, 0xf0
	v_or_b32_e32 v6, s64, v6
	v_or_b32_e32 v14, s64, v14
	v_cndmask_b32_e64 v18, v18, 15, vcc
	v_mul_lo_u32 v6, v6, s12
	v_mov_b32_e32 v7, v129
	v_mul_lo_u32 v14, v14, s12
	v_mov_b32_e32 v15, v129
	v_or_b32_e32 v18, s64, v18
	v_lshl_add_u64 v[6:7], v[6:7], 1, s[56:57]
	v_lshl_add_u64 v[14:15], v[14:15], 1, s[56:57]
	v_mul_lo_u32 v18, v18, s12
	v_mov_b32_e32 v19, v129
	v_lshl_add_u64 v[12:13], v[6:7], 0, v[4:5]
	v_lshl_add_u64 v[16:17], v[14:15], 0, v[4:5]
	v_lshl_add_u64 v[14:15], v[14:15], 0, v[2:3]
	v_lshl_add_u64 v[18:19], v[18:19], 1, s[56:57]
	v_lshl_add_u64 v[6:7], v[6:7], 0, v[2:3]
	v_lshl_add_u64 v[20:21], v[18:19], 0, v[4:5]
	global_load_ushort v196, v[12:13], off offset:1536
	global_load_ushort v198, v[6:7], off
	global_load_ushort v195, v[16:17], off offset:1536
	global_load_ushort v197, v[14:15], off
	global_load_ushort v194, v[20:21], off offset:1536
	global_load_ushort v199, v[20:21], off offset:3072
	global_load_ushort v209, v[16:17], off offset:3072
	global_load_ushort v210, v[12:13], off offset:3072
	v_mov_b32_e32 v14, 0xef
	v_lshl_add_u64 v[12:13], v[18:19], 0, v[2:3]
	v_readlane_b32 s12, v255, 26
	v_cndmask_b32_e64 v14, v14, 16, vcc
	v_mov_b32_e32 v18, 0xee
	v_readlane_b32 s13, v255, 27
	v_or_b32_e32 v14, s64, v14
	v_cndmask_b32_e64 v18, v18, 17, vcc
	v_mov_b32_e32 v22, 0xed
	v_lshl_add_u64 v[6:7], s[12:13], 0, v[128:129]
	v_mul_lo_u32 v128, v14, s23
	v_or_b32_e32 v18, s64, v18
	v_cndmask_b32_e64 v22, v22, 18, vcc
	v_lshl_add_u64 v[14:15], s[56:57], 0, v[128:129]
	v_mul_lo_u32 v128, v18, s23
	v_or_b32_e32 v22, s64, v22
	v_lshl_add_u64 v[18:19], s[56:57], 0, v[128:129]
	v_mul_lo_u32 v128, v22, s23
	v_lshl_add_u64 v[16:17], v[14:15], 0, v[4:5]
	v_lshl_add_u64 v[14:15], v[14:15], 0, v[2:3]
	v_lshl_add_u64 v[22:23], s[56:57], 0, v[128:129]
	s_waitcnt vmcnt(47)
	v_sub_f32_e32 v136, 1.0, v24
	v_lshl_add_u64 v[20:21], v[18:19], 0, v[4:5]
	v_lshl_add_u64 v[18:19], v[18:19], 0, v[2:3]
	v_lshl_add_u64 v[24:25], v[22:23], 0, v[4:5]
	global_load_ushort v211, v[12:13], off
	global_load_ushort v214, v[16:17], off offset:1536
	global_load_ushort v216, v[14:15], off
	global_load_ushort v213, v[20:21], off offset:1536
	global_load_ushort v215, v[18:19], off
	global_load_ushort v212, v[24:25], off offset:1536
	global_load_ushort v217, v[20:21], off offset:3072
	global_load_ushort v218, v[16:17], off offset:3072
	v_mov_b32_e32 v14, 0xec
	v_cndmask_b32_e64 v14, v14, 19, vcc
	v_mov_b32_e32 v18, 0xeb
	v_or_b32_e32 v14, s64, v14
	v_cndmask_b32_e64 v18, v18, 20, vcc
	v_mul_lo_u32 v128, v14, s23
	v_or_b32_e32 v18, s64, v18
	v_lshl_add_u64 v[14:15], s[56:57], 0, v[128:129]
	v_mul_lo_u32 v128, v18, s23
	v_lshl_add_u64 v[12:13], v[22:23], 0, v[2:3]
	v_lshl_add_u64 v[18:19], s[56:57], 0, v[128:129]
	v_lshl_add_u64 v[16:17], v[14:15], 0, v[4:5]
	v_lshl_add_u64 v[14:15], v[14:15], 0, v[2:3]
	v_lshl_add_u64 v[20:21], v[18:19], 0, v[4:5]
	v_lshl_add_u64 v[18:19], v[18:19], 0, v[2:3]
	global_load_ushort v224, v[12:13], off
	global_load_ushort v220, v[16:17], off offset:1536
	global_load_ushort v222, v[14:15], off
	global_load_ushort v219, v[20:21], off offset:1536
	global_load_ushort v221, v[18:19], off
	global_load_ushort v223, v[20:21], off offset:3072
	global_load_ushort v225, v[16:17], off offset:3072
	global_load_ushort v226, v[24:25], off offset:3072
	v_mov_b32_e32 v12, 0xea
	v_cndmask_b32_e64 v12, v12, 21, vcc
	v_mov_b32_e32 v16, 0xe9
	v_or_b32_e32 v12, s64, v12
	v_cndmask_b32_e64 v16, v16, 22, vcc
	v_mov_b32_e32 v20, 0xe8
	v_mul_lo_u32 v128, v12, s23
	v_or_b32_e32 v16, s64, v16
	v_cndmask_b32_e64 v20, v20, 23, vcc
	v_lshl_add_u64 v[12:13], s[56:57], 0, v[128:129]
	v_mul_lo_u32 v128, v16, s23
	v_or_b32_e32 v20, s64, v20
	v_lshl_add_u64 v[16:17], s[56:57], 0, v[128:129]
	v_mul_lo_u32 v128, v20, s23
	v_lshl_add_u64 v[14:15], v[12:13], 0, v[4:5]
	v_lshl_add_u64 v[20:21], s[56:57], 0, v[128:129]
	v_lshl_add_u64 v[12:13], v[12:13], 0, v[2:3]
	v_lshl_add_u64 v[18:19], v[16:17], 0, v[4:5]
	v_lshl_add_u64 v[16:17], v[16:17], 0, v[2:3]
	v_lshl_add_u64 v[22:23], v[20:21], 0, v[4:5]
; #define HM_LOAD(RQ, RZ, RV, j_) do { _Pragma("unroll") for (int i = 0; i < 16; ++i) { const bf16_t* pr_ = proj + HM_TOK((j_) * 16 + i) * INW; RQ[i] = pr_[qc]; RZ[i] = pr_[zc]; RV[i] = pr_[vc]; } } while (0)
; __device__ __forceinline__ void hgrn_mfma_unit(const Params& P, int l, LAS unsigned char* lds, int b, int half) {
;     ...
;         unsigned aq[16], az[16], av[16], bq[16], bz[16], bv[16];
;         HM_LOAD(aq, az, av, 0); HM_LOAD(bq, bz, bv, 1);
;         f32x4 S[4][4];
; #pragma unroll
;         for (int mb = 0; mb < 4; ++mb)
; #pragma unroll
;             for (int nb = 0; nb < 4; ++nb) S[mb][nb] = (f32x4){0.f, 0.f, 0.f, 0.f};
;         f32x4 o[4];
	global_load_ushort v229, v[14:15], off offset:1536
	global_load_ushort v231, v[12:13], off
	global_load_ushort v228, v[18:19], off offset:1536
	global_load_ushort v230, v[16:17], off
	global_load_ushort v227, v[22:23], off offset:1536
	global_load_ushort v232, v[22:23], off offset:3072
	global_load_ushort v233, v[18:19], off offset:3072
	global_load_ushort v234, v[14:15], off offset:3072
	v_mov_b32_e32 v14, 0xe7
	v_cndmask_b32_e64 v14, v14, 24, vcc
	v_mov_b32_e32 v18, 0xe6
	v_or_b32_e32 v14, s64, v14
	v_cndmask_b32_e64 v18, v18, 25, vcc
	v_mov_b32_e32 v22, 0xe5
	v_mul_lo_u32 v128, v14, s23
	v_or_b32_e32 v18, s64, v18
	v_cndmask_b32_e64 v22, v22, 26, vcc
	v_lshl_add_u64 v[14:15], s[56:57], 0, v[128:129]
	v_mul_lo_u32 v128, v18, s23
	v_or_b32_e32 v22, s64, v22
	v_lshl_add_u64 v[18:19], s[56:57], 0, v[128:129]
	v_mul_lo_u32 v128, v22, s23
	v_lshl_add_u64 v[12:13], v[20:21], 0, v[2:3]
	v_lshl_add_u64 v[16:17], v[14:15], 0, v[4:5]
	v_lshl_add_u64 v[14:15], v[14:15], 0, v[2:3]
	v_lshl_add_u64 v[22:23], s[56:57], 0, v[128:129]
	v_lshl_add_u64 v[20:21], v[18:19], 0, v[4:5]
	v_lshl_add_u64 v[18:19], v[18:19], 0, v[2:3]
	v_lshl_add_u64 v[24:25], v[22:23], 0, v[4:5]
	global_load_ushort v240, v[12:13], off
	global_load_ushort v237, v[16:17], off offset:1536
	global_load_ushort v239, v[14:15], off
	global_load_ushort v236, v[20:21], off offset:1536
	global_load_ushort v238, v[18:19], off
	global_load_ushort v235, v[24:25], off offset:1536
	global_load_ushort v241, v[20:21], off offset:3072
	global_load_ushort v242, v[16:17], off offset:3072
	v_mov_b32_e32 v14, 0xe4
	v_cndmask_b32_e64 v14, v14, 27, vcc
	v_mov_b32_e32 v18, 0xe3
	v_or_b32_e32 v14, s64, v14
	v_cndmask_b32_e64 v18, v18, 28, vcc
	v_mul_lo_u32 v128, v14, s23
	v_or_b32_e32 v18, s64, v18
	v_lshl_add_u64 v[14:15], s[56:57], 0, v[128:129]
	v_mul_lo_u32 v128, v18, s23
	v_lshl_add_u64 v[12:13], v[22:23], 0, v[2:3]
	v_lshl_add_u64 v[18:19], s[56:57], 0, v[128:129]
	v_lshl_add_u64 v[16:17], v[14:15], 0, v[4:5]
	v_lshl_add_u64 v[14:15], v[14:15], 0, v[2:3]
	v_lshl_add_u64 v[20:21], v[18:19], 0, v[4:5]
	v_lshl_add_u64 v[18:19], v[18:19], 0, v[2:3]
	global_load_ushort v248, v[12:13], off
	global_load_ushort v244, v[16:17], off offset:1536
	global_load_ushort v246, v[14:15], off
	global_load_ushort v243, v[20:21], off offset:1536
	global_load_ushort v245, v[18:19], off
	global_load_ushort v247, v[20:21], off offset:3072
	global_load_ushort v249, v[16:17], off offset:3072
	global_load_ushort v250, v[24:25], off offset:3072
	v_mov_b32_e32 v12, 0xe2
	v_cndmask_b32_e64 v12, v12, 29, vcc
	v_mov_b32_e32 v16, 0xe1
	v_or_b32_e32 v12, s64, v12
	v_cndmask_b32_e64 v16, v16, 30, vcc
	v_mov_b32_e32 v20, 0xe0
	v_mul_lo_u32 v128, v12, s23
	v_or_b32_e32 v16, s64, v16
	v_cndmask_b32_e64 v20, v20, 31, vcc
	v_lshl_add_u64 v[12:13], s[56:57], 0, v[128:129]
	v_mul_lo_u32 v128, v16, s23
	v_or_b32_e32 v20, s64, v20
	v_lshl_add_u64 v[16:17], s[56:57], 0, v[128:129]
	v_mul_lo_u32 v128, v20, s23
	v_lshl_add_u64 v[14:15], v[12:13], 0, v[4:5]
	v_lshl_add_u64 v[20:21], s[56:57], 0, v[128:129]
	v_lshl_add_u64 v[12:13], v[12:13], 0, v[2:3]
	v_lshl_add_u64 v[18:19], v[16:17], 0, v[4:5]
	v_lshl_add_u64 v[16:17], v[16:17], 0, v[2:3]
	v_lshl_add_u64 v[4:5], v[20:21], 0, v[4:5]
	global_load_ushort v205, v[14:15], off offset:1536
	global_load_ushort v206, v[12:13], off
	global_load_ushort v252, v[18:19], off offset:1536
	global_load_ushort v204, v[16:17], off
	global_load_ushort v251, v[4:5], off offset:1536
	global_load_ushort v208, v[4:5], off offset:3072
	global_load_ushort v179, v[18:19], off offset:3072
	global_load_ushort v180, v[14:15], off offset:3072
	v_lshl_add_u64 v[2:3], v[20:21], 0, v[2:3]
	global_load_ushort v178, v[2:3], off
	v_bfe_u32 v10, v8, 4, 2
	v_and_b32_e32 v142, 15, v8
	v_and_b32_e32 v138, 48, v8
	v_lshlrev_b32_e32 v4, 2, v10
	v_lshl_add_u64 v[0:1], v[6:7], 0, v[0:1]
	v_mov_b32_e32 v139, v129
	v_add_u32_e32 v133, 0, v11
	v_lshlrev_b32_e32 v2, 1, v9
	v_lshlrev_b32_e32 v3, 5, v9
	s_movk_i32 s7, 0x90
	v_cmp_gt_u32_e64 s[40:41], v4, v142
	v_cmp_lt_u32_e64 s[42:43], v4, v142
	v_or_b32_e32 v5, 2, v4
	v_or_b32_e32 v4, 3, v4
	v_lshl_add_u64 v[140:141], v[0:1], 0, v[138:139]
	v_mov_b32_e32 v0, 0
	s_mov_b32 s8, 63
	s_mov_b32 s9, 0
	v_mad_u32_u24 v143, v142, s7, v133
	v_cmp_gt_u32_e64 s[44:45], v5, v142
	v_cmp_gt_u32_e64 s[46:47], v4, v142
	v_lshlrev_b32_e32 v144, 3, v10
	v_lshl_add_u32 v145, v142, 5, v133
	v_cmp_gt_u32_e64 s[48:49], 32, v9
	v_mov_b32_e32 v137, v136
	v_add_u32_e32 v139, v133, v2
	v_add_u32_e32 v146, v133, v3
	v_mov_b32_e32 v1, v0
	v_mov_b32_e32 v2, v0
	v_mov_b32_e32 v3, v0
	v_mov_b32_e32 v4, v0
	v_mov_b32_e32 v5, v0
	v_mov_b32_e32 v6, v0
	v_mov_b32_e32 v7, v0
	v_mov_b32_e32 v8, v0
	v_mov_b32_e32 v9, v0
	v_mov_b32_e32 v10, v0
	v_mov_b32_e32 v11, v0
	v_mov_b32_e32 v12, v0
	v_mov_b32_e32 v13, v0
	v_mov_b32_e32 v14, v0
	v_mov_b32_e32 v15, v0
	v_mov_b32_e32 v16, v0
	v_mov_b32_e32 v17, v0
	v_mov_b32_e32 v18, v0
	v_mov_b32_e32 v19, v0
	v_mov_b32_e32 v20, v0
	v_mov_b32_e32 v21, v0
	v_mov_b32_e32 v22, v0
	v_mov_b32_e32 v23, v0
	v_mov_b32_e32 v24, v0
	v_mov_b32_e32 v25, v0
	v_mov_b32_e32 v26, v0
	v_mov_b32_e32 v27, v0
	v_mov_b32_e32 v28, v0
	v_mov_b32_e32 v29, v0
	v_mov_b32_e32 v30, v0
	v_mov_b32_e32 v31, v0
	v_mov_b32_e32 v32, v0
	v_mov_b32_e32 v33, v0
	v_mov_b32_e32 v34, v0
	v_mov_b32_e32 v35, v0
	v_mov_b32_e32 v36, v0
	v_mov_b32_e32 v37, v0
	v_mov_b32_e32 v38, v0
	v_mov_b32_e32 v39, v0
	v_mov_b32_e32 v40, v0
	v_mov_b32_e32 v41, v0
	v_mov_b32_e32 v42, v0
	v_mov_b32_e32 v43, v0
	v_mov_b32_e32 v44, v0
	v_mov_b32_e32 v45, v0
	v_mov_b32_e32 v46, v0
	v_mov_b32_e32 v47, v0
	v_mov_b32_e32 v48, v0
	v_mov_b32_e32 v49, v0
	v_mov_b32_e32 v50, v0
	v_mov_b32_e32 v51, v0
	v_mov_b32_e32 v52, v0
	v_mov_b32_e32 v53, v0
	v_mov_b32_e32 v54, v0
	v_mov_b32_e32 v55, v0
	v_mov_b32_e32 v56, v0
	v_mov_b32_e32 v57, v0
	v_mov_b32_e32 v58, v0
	v_mov_b32_e32 v59, v0
	v_mov_b32_e32 v60, v0
	v_mov_b32_e32 v61, v0
	v_mov_b32_e32 v62, v0
	v_mov_b32_e32 v63, v0
	s_branch .LBB0_465

; #define LAS __attribute__((address_space(3)))
; __device__ __forceinline__ unsigned pk2(float lo, float hi) { f32x2_t v = {lo, hi}; bf16x2_t b = __builtin_convertvector(v, bf16x2_t); return __builtin_bit_cast(unsigned, b); }
; __device__ __forceinline__ float fast_exp2(float x) { return __builtin_amdgcn_exp2f(x); }
; __device__ __forceinline__ void hm_stage(LAS unsigned char* wl, const unsigned (&rq)[16], const unsigned (&rz)[16], const unsigned (&rv)[16], float oml, int lane) {
;     ...
;     for (int i = 0; i < 16; ++i) {
;         const float z = bf2f(rz[i]), q = bf2f(rq[i]);
;         const float sg = __builtin_amdgcn_rcpf(1.0f + fast_exp2(z * LOG2E));
;         const float k = oml * sg;
;         run = fmaxf(run * (1.0f - k), 8.673617379884035e-19f);
;         const float ieb = __builtin_amdgcn_rcpf(run);
;         kt[i] = k * ieb;
;         *(LAS unsigned short*)(wl + HM_QT + i * HM_QP + lane * 2) = (unsigned short)pk2(q * run, 0.f);
;         *(LAS unsigned short*)(wl + HM_KT + i * HM_QP + lane * 2) = (unsigned short)pk2(kt[i], 0.f);
;         if (i & 1) vpk[i >> 1] = rv[i - 1] | (rv[i] << 16);
;     }
;     const float eB = run;
;     *(LAS float*)(wl + HM_EB + lane * 4) = eB;
.LBB0_465:
	s_waitcnt vmcnt(48)
	s_add_u32 s100, s9, 2
	s_min_u32 s100, s100, 142
	s_lshl_b32 s12, s100, 4
	s_mov_b32 s18, 0x1600
	s_mov_b32 s19, 0
	s_cmp_eq_u64 s[38:39], 0
	s_cbranch_scc1 .Lhe_a0
	s_cmp_lt_u32 s100, 16
	s_movk_i32 s13, 0x9ff
	s_cselect_b32 s13, 0xff, s13
	s_sub_u32 s12, s13, s12
	s_mov_b32 s18, 0xffffea00
	s_mov_b32 s19, -1
.Lhe_a0:
	s_add_u32 s12, s12, s64
	s_mul_i32 s12, s12, 0x1600
	s_add_u32 s12, s56, s12
	s_addc_u32 s13, s57, 0
	v_lshlrev_b32_e32 v64, 16, v151
	v_mul_f32_e32 v64, 0x3fb8aa3b, v64
	v_exp_f32_e32 v64, v64
	v_lshlrev_b32_e32 v89, 16, v149
	global_load_ushort v149, v130, s[12:13] offset:1536
	global_load_ushort v151, v134, s[12:13]
	s_add_u32 s12, s12, s18
	s_addc_u32 s13, s13, s19
	v_lshlrev_b32_e32 v90, 16, v148
	v_lshlrev_b32_e32 v91, 16, v147
	v_add_f32_e32 v64, 1.0, v64
	v_rcp_f32_e32 v74, v64
	v_lshlrev_b32_e32 v64, 16, v150
	global_load_ushort v148, v130, s[12:13] offset:1536
	global_load_ushort v150, v134, s[12:13]
	s_add_u32 s12, s12, s18
	s_addc_u32 s13, s13, s19
	v_mul_f32_e32 v64, 0x3fb8aa3b, v64
	v_exp_f32_e32 v64, v64
	v_lshlrev_b32_e32 v92, 16, v155
	v_lshlrev_b32_e32 v93, 16, v154
	v_lshlrev_b32_e32 v94, 16, v164
	v_add_f32_e32 v64, 1.0, v64
	v_rcp_f32_e32 v75, v64
	v_lshlrev_b32_e32 v64, 16, v158
	global_load_ushort v147, v130, s[12:13] offset:1536
	global_load_ushort v158, v134, s[12:13]
	s_add_u32 s12, s12, s18
	s_addc_u32 s13, s13, s19
	v_mul_f32_e32 v64, 0x3fb8aa3b, v64
	v_exp_f32_e32 v64, v64
	v_pk_mul_f32 v[74:75], v[136:137], v[74:75]
	v_lshlrev_b32_e32 v95, 16, v163
	v_sub_f32_e32 v88, 1.0, v74
	v_max_f32_e32 v119, 0x21800000, v88
	v_add_f32_e32 v64, 1.0, v64
	v_mul_f32_e32 v89, v119, v89
	v_rcp_f32_e32 v78, v64
	v_lshlrev_b32_e32 v64, 16, v157
	global_load_ushort v155, v130, s[12:13] offset:1536
	global_load_ushort v157, v134, s[12:13]
	s_add_u32 s12, s12, s18
	s_addc_u32 s13, s13, s19
	v_cvt_pk_bf16_f32 v89, v89, s0
	v_mul_f32_e32 v64, 0x3fb8aa3b, v64
	ds_write_b16 v139, v89
	v_sub_f32_e32 v89, 1.0, v75
	v_exp_f32_e32 v64, v64
	v_mul_f32_e32 v89, v89, v119
	v_rcp_f32_e32 v88, v119
	v_max_f32_e32 v119, 0x21800000, v89
	v_rcp_f32_e32 v89, v119
	v_add_f32_e32 v64, 1.0, v64
	v_rcp_f32_e32 v79, v64
	v_lshlrev_b32_e32 v64, 16, v156
	global_load_ushort v154, v130, s[12:13] offset:1536
	global_load_ushort v156, v134, s[12:13]
	s_add_u32 s12, s12, s18
	s_addc_u32 s13, s13, s19
	v_mul_f32_e32 v64, 0x3fb8aa3b, v64
	v_pk_mul_f32 v[74:75], v[74:75], v[88:89]
	v_exp_f32_e32 v64, v64
	v_cvt_pk_bf16_f32 v88, v74, s0
	ds_write_b16 v139, v88 offset:2304
	v_mul_f32_e32 v88, v119, v90
	v_pk_mul_f32 v[78:79], v[136:137], v[78:79]
	v_cvt_pk_bf16_f32 v88, v88, s0
	v_sub_f32_e32 v117, 1.0, v78
	ds_write_b16 v139, v88 offset:144
	v_cvt_pk_bf16_f32 v88, v75, s0
	v_add_f32_e32 v64, 1.0, v64
	ds_write_b16 v139, v88 offset:2448
	v_mul_f32_e32 v88, v117, v119
	v_rcp_f32_e32 v82, v64
	v_lshlrev_b32_e32 v64, 16, v166
	global_load_ushort v164, v130, s[12:13] offset:1536
	global_load_ushort v166, v134, s[12:13]
	s_add_u32 s12, s12, s18
	s_addc_u32 s13, s13, s19
	v_max_f32_e32 v89, 0x21800000, v88
	v_mul_f32_e32 v64, 0x3fb8aa3b, v64
	v_sub_f32_e32 v118, 1.0, v79
	v_mul_f32_e32 v90, v89, v91
	v_exp_f32_e32 v64, v64
	v_rcp_f32_e32 v88, v89
	v_cvt_pk_bf16_f32 v90, v90, s0
	v_mul_f32_e32 v89, v118, v89
	ds_write_b16 v139, v90 offset:288
	v_max_f32_e32 v90, 0x21800000, v89
	v_rcp_f32_e32 v89, v90
	v_add_f32_e32 v64, 1.0, v64
	v_rcp_f32_e32 v83, v64
	v_lshlrev_b32_e32 v64, 16, v165
	global_load_ushort v163, v130, s[12:13] offset:1536
	global_load_ushort v165, v134, s[12:13]
	s_add_u32 s12, s12, s18
	s_addc_u32 s13, s13, s19
	v_mul_f32_e32 v64, 0x3fb8aa3b, v64
	v_pk_mul_f32 v[78:79], v[78:79], v[88:89]
	v_exp_f32_e32 v64, v64
	v_cvt_pk_bf16_f32 v88, v78, s0
	ds_write_b16 v139, v88 offset:2592
	v_mul_f32_e32 v88, v90, v92
	v_pk_mul_f32 v[82:83], v[136:137], v[82:83]
	v_cvt_pk_bf16_f32 v88, v88, s0
	v_sub_f32_e32 v115, 1.0, v82
	ds_write_b16 v139, v88 offset:432
	v_cvt_pk_bf16_f32 v88, v79, s0
	v_add_f32_e32 v64, 1.0, v64
	ds_write_b16 v139, v88 offset:2736
	v_mul_f32_e32 v88, v115, v90
	v_rcp_f32_e32 v84, v64
	v_lshlrev_b32_e32 v64, 16, v175
	v_max_f32_e32 v89, 0x21800000, v88
	v_mul_f32_e32 v64, 0x3fb8aa3b, v64
	v_sub_f32_e32 v116, 1.0, v83
	v_mul_f32_e32 v90, v89, v93
	v_exp_f32_e32 v64, v64
	v_rcp_f32_e32 v88, v89
	v_cvt_pk_bf16_f32 v90, v90, s0
	v_mul_f32_e32 v89, v116, v89
	ds_write_b16 v139, v90 offset:576
	v_max_f32_e32 v90, 0x21800000, v89
	v_rcp_f32_e32 v89, v90
	v_add_f32_e32 v64, 1.0, v64
	v_rcp_f32_e32 v85, v64
	v_lshlrev_b32_e32 v64, 16, v174
	v_mul_f32_e32 v64, 0x3fb8aa3b, v64
	v_pk_mul_f32 v[82:83], v[82:83], v[88:89]
	v_exp_f32_e32 v64, v64
	v_cvt_pk_bf16_f32 v88, v82, s0
	ds_write_b16 v139, v88 offset:2880
	v_mul_f32_e32 v88, v90, v94
	v_pk_mul_f32 v[84:85], v[136:137], v[84:85]
	v_cvt_pk_bf16_f32 v88, v88, s0
	v_sub_f32_e32 v113, 1.0, v84
	ds_write_b16 v139, v88 offset:720
	v_cvt_pk_bf16_f32 v88, v83, s0
	v_add_f32_e32 v64, 1.0, v64
	ds_write_b16 v139, v88 offset:3024
	v_mul_f32_e32 v88, v113, v90
	v_rcp_f32_e32 v86, v64
	v_lshlrev_b32_e32 v64, 16, v173
	v_max_f32_e32 v89, 0x21800000, v88
	v_mul_f32_e32 v64, 0x3fb8aa3b, v64
	v_sub_f32_e32 v114, 1.0, v85
	v_mul_f32_e32 v90, v89, v95
	v_exp_f32_e32 v64, v64
	v_rcp_f32_e32 v88, v89
	v_cvt_pk_bf16_f32 v90, v90, s0
	v_mul_f32_e32 v89, v114, v89
	ds_write_b16 v139, v90 offset:864
	v_max_f32_e32 v90, 0x21800000, v89
	v_rcp_f32_e32 v89, v90
	v_add_f32_e32 v64, 1.0, v64
	v_rcp_f32_e32 v87, v64
	v_lshlrev_b32_e32 v64, 16, v190
	v_mul_f32_e32 v64, 0x3fb8aa3b, v64
	v_pk_mul_f32 v[84:85], v[84:85], v[88:89]
	v_lshlrev_b32_e32 v96, 16, v162
; #define LAS __attribute__((address_space(3)))
; __device__ __forceinline__ unsigned pk2(float lo, float hi) { f32x2_t v = {lo, hi}; bf16x2_t b = __builtin_convertvector(v, bf16x2_t); return __builtin_bit_cast(unsigned, b); }
; __device__ __forceinline__ float fast_exp2(float x) { return __builtin_amdgcn_exp2f(x); }
; #define HM_LOAD(RQ, RZ, RV, j_) do { _Pragma("unroll") for (int i = 0; i < 16; ++i) { const bf16_t* pr_ = proj + HM_TOK((j_) * 16 + i) * INW; RQ[i] = pr_[qc]; RZ[i] = pr_[zc]; RV[i] = pr_[vc]; } } while (0)
; __device__ __forceinline__ void hm_stage(LAS unsigned char* wl, const unsigned (&rq)[16], const unsigned (&rz)[16], const unsigned (&rv)[16], float oml, int lane) {
;     ...
;     for (int i = 0; i < 16; ++i) {
;         const float z = bf2f(rz[i]), q = bf2f(rq[i]);
;         const float sg = __builtin_amdgcn_rcpf(1.0f + fast_exp2(z * LOG2E));
;         const float k = oml * sg;
;         run = fmaxf(run * (1.0f - k), 8.673617379884035e-19f);
;         const float ieb = __builtin_amdgcn_rcpf(run);
;         kt[i] = k * ieb;
;         *(LAS unsigned short*)(wl + HM_QT + i * HM_QP + lane * 2) = (unsigned short)pk2(q * run, 0.f);
;         *(LAS unsigned short*)(wl + HM_KT + i * HM_QP + lane * 2) = (unsigned short)pk2(kt[i], 0.f);
;         if (i & 1) vpk[i >> 1] = rv[i - 1] | (rv[i] << 16);
;     }
;     const float eB = run;
;     *(LAS float*)(wl + HM_EB + lane * 4) = eB;
;     u32x4 w0, w1;
;     w0.x = pk2(kt[0] * eB, kt[1] * eB); w0.y = pk2(kt[2] * eB, kt[3] * eB); w0.z = pk2(kt[4] * eB, kt[5] * eB); w0.w = pk2(kt[6] * eB, kt[7] * eB);
;     w1.x = pk2(kt[8] * eB, kt[9] * eB); w1.y = pk2(kt[10] * eB, kt[11] * eB); w1.z = pk2(kt[12] * eB, kt[13] * eB); w1.w = pk2(kt[14] * eB, kt[15] * eB);
;     *(LAS u32x4*)(wl + HM_KD + lane * 32) = w0; *(LAS u32x4*)(wl + HM_KD + lane * 32 + 16) = w1;
;     *(LAS u32x4*)(wl + HM_VT + lane * 32) = (u32x4){vpk[0], vpk[1], vpk[2], vpk[3]}; *(LAS u32x4*)(wl + HM_VT + lane * 32 + 16) = (u32x4){vpk[4], vpk[5], vpk[6], vpk[7]};
; __device__ __forceinline__ void hgrn_mfma_unit(const Params& P, int l, LAS unsigned char* lds, int b, int half) {
;     ...
;             if (j + 2 < NSC) HM_LOAD(aq, az, av, j + 2);
	global_load_ushort v162, v130, s[12:13] offset:1536
	global_load_ushort v175, v134, s[12:13]
	s_add_u32 s12, s12, s18
	s_addc_u32 s13, s13, s19
	v_exp_f32_e32 v64, v64
	v_cvt_pk_bf16_f32 v88, v84, s0
	ds_write_b16 v139, v88 offset:3168
	v_mul_f32_e32 v88, v90, v96
	v_pk_mul_f32 v[86:87], v[136:137], v[86:87]
	v_cvt_pk_bf16_f32 v88, v88, s0
	v_sub_f32_e32 v111, 1.0, v86
	ds_write_b16 v139, v88 offset:1008
	v_cvt_pk_bf16_f32 v88, v85, s0
	v_add_f32_e32 v64, 1.0, v64
	ds_write_b16 v139, v88 offset:3312
	v_mul_f32_e32 v88, v111, v90
	v_lshlrev_b32_e32 v97, 16, v172
	global_load_ushort v172, v130, s[12:13] offset:1536
	global_load_ushort v174, v134, s[12:13]
	s_add_u32 s12, s12, s18
	s_addc_u32 s13, s13, s19
	v_rcp_f32_e32 v80, v64
	v_lshlrev_b32_e32 v64, 16, v189
	v_max_f32_e32 v89, 0x21800000, v88
	v_mul_f32_e32 v64, 0x3fb8aa3b, v64
	v_sub_f32_e32 v112, 1.0, v87
	v_mul_f32_e32 v90, v89, v97
	v_exp_f32_e32 v64, v64
	v_rcp_f32_e32 v88, v89
	v_cvt_pk_bf16_f32 v90, v90, s0
	v_mul_f32_e32 v89, v112, v89
	ds_write_b16 v139, v90 offset:1152
	v_max_f32_e32 v90, 0x21800000, v89
	v_rcp_f32_e32 v89, v90
	v_add_f32_e32 v64, 1.0, v64
	v_rcp_f32_e32 v81, v64
	v_lshlrev_b32_e32 v64, 16, v188
	v_mul_f32_e32 v64, 0x3fb8aa3b, v64
	v_pk_mul_f32 v[86:87], v[86:87], v[88:89]
	v_lshlrev_b32_e32 v98, 16, v171
	global_load_ushort v171, v130, s[12:13] offset:1536
	global_load_ushort v173, v134, s[12:13]
	s_add_u32 s12, s12, s18
	s_addc_u32 s13, s13, s19
	v_exp_f32_e32 v64, v64
	v_cvt_pk_bf16_f32 v88, v86, s0
	ds_write_b16 v139, v88 offset:3456
	v_mul_f32_e32 v88, v90, v98
	v_pk_mul_f32 v[80:81], v[136:137], v[80:81]
	v_cvt_pk_bf16_f32 v88, v88, s0
	v_sub_f32_e32 v109, 1.0, v80
	ds_write_b16 v139, v88 offset:1296
	v_cvt_pk_bf16_f32 v88, v87, s0
	v_add_f32_e32 v64, 1.0, v64
	ds_write_b16 v139, v88 offset:3600
	v_mul_f32_e32 v88, v109, v90
	v_lshlrev_b32_e32 v99, 16, v170
	global_load_ushort v170, v130, s[12:13] offset:1536
	global_load_ushort v190, v134, s[12:13]
	s_add_u32 s12, s12, s18
	s_addc_u32 s13, s13, s19
	v_rcp_f32_e32 v76, v64
	v_lshlrev_b32_e32 v64, 16, v198
	v_max_f32_e32 v89, 0x21800000, v88
	v_mul_f32_e32 v64, 0x3fb8aa3b, v64
	v_sub_f32_e32 v110, 1.0, v81
	v_mul_f32_e32 v90, v89, v99
	v_exp_f32_e32 v64, v64
	v_rcp_f32_e32 v88, v89
	v_cvt_pk_bf16_f32 v90, v90, s0
	v_mul_f32_e32 v89, v110, v89
	ds_write_b16 v139, v90 offset:1440
	v_max_f32_e32 v90, 0x21800000, v89
	v_rcp_f32_e32 v89, v90
	v_add_f32_e32 v64, 1.0, v64
	v_rcp_f32_e32 v77, v64
	v_lshlrev_b32_e32 v64, 16, v197
	v_mul_f32_e32 v64, 0x3fb8aa3b, v64
	v_pk_mul_f32 v[80:81], v[80:81], v[88:89]
	v_lshlrev_b32_e32 v100, 16, v187
	global_load_ushort v187, v130, s[12:13] offset:1536
	global_load_ushort v189, v134, s[12:13]
	s_add_u32 s12, s12, s18
	s_addc_u32 s13, s13, s19
	v_exp_f32_e32 v64, v64
	v_cvt_pk_bf16_f32 v88, v80, s0
	ds_write_b16 v139, v88 offset:3744
	v_mul_f32_e32 v88, v90, v100
	v_pk_mul_f32 v[76:77], v[136:137], v[76:77]
	v_cvt_pk_bf16_f32 v88, v88, s0
	v_sub_f32_e32 v107, 1.0, v76
	ds_write_b16 v139, v88 offset:1584
	v_cvt_pk_bf16_f32 v88, v81, s0
	v_add_f32_e32 v64, 1.0, v64
	ds_write_b16 v139, v88 offset:3888
	v_mul_f32_e32 v88, v107, v90
	v_lshlrev_b32_e32 v101, 16, v186
	global_load_ushort v186, v130, s[12:13] offset:1536
	global_load_ushort v188, v134, s[12:13]
	s_add_u32 s12, s12, s18
	s_addc_u32 s13, s13, s19
	v_rcp_f32_e32 v72, v64
	v_lshlrev_b32_e32 v64, 16, v211
	v_max_f32_e32 v89, 0x21800000, v88
	v_mul_f32_e32 v64, 0x3fb8aa3b, v64
	v_sub_f32_e32 v108, 1.0, v77
	v_mul_f32_e32 v90, v89, v101
	v_exp_f32_e32 v64, v64
	v_rcp_f32_e32 v88, v89
	v_cvt_pk_bf16_f32 v90, v90, s0
	v_mul_f32_e32 v89, v108, v89
	ds_write_b16 v139, v90 offset:1728
	v_max_f32_e32 v90, 0x21800000, v89
	v_rcp_f32_e32 v89, v90
	v_add_f32_e32 v64, 1.0, v64
	v_rcp_f32_e32 v73, v64
	v_lshlrev_b32_e32 v102, 16, v196
	global_load_ushort v196, v130, s[12:13] offset:1536
	global_load_ushort v198, v134, s[12:13]
	s_add_u32 s12, s12, s18
	s_addc_u32 s13, s13, s19
	v_pk_mul_f32 v[88:89], v[76:77], v[88:89]
	v_lshlrev_b32_e32 v103, 16, v195
	global_load_ushort v195, v130, s[12:13] offset:1536
	global_load_ushort v197, v134, s[12:13]
	s_add_u32 s12, s12, s18
	s_addc_u32 s13, s13, s19
	v_cvt_pk_bf16_f32 v76, v88, s0
	ds_write_b16 v139, v76 offset:4032
	v_mul_f32_e32 v76, v90, v102
	v_pk_mul_f32 v[72:73], v[136:137], v[72:73]
	v_cvt_pk_bf16_f32 v76, v76, s0
	v_sub_f32_e32 v105, 1.0, v72
	ds_write_b16 v139, v76 offset:1872
	v_cvt_pk_bf16_f32 v76, v89, s0
	ds_write_b16 v139, v76 offset:4176
	v_mul_f32_e32 v76, v105, v90
	v_max_f32_e32 v77, 0x21800000, v76
	v_sub_f32_e32 v106, 1.0, v73
	v_mul_f32_e32 v90, v77, v103
	v_rcp_f32_e32 v76, v77
	v_cvt_pk_bf16_f32 v90, v90, s0
	v_mul_f32_e32 v77, v106, v77
	ds_write_b16 v139, v90 offset:2016
	v_max_f32_e32 v90, 0x21800000, v77
	v_rcp_f32_e32 v77, v90
	v_lshlrev_b32_e32 v104, 16, v194
	global_load_ushort v194, v130, s[12:13] offset:1536
	global_load_ushort v211, v134, s[12:13]
	s_add_u32 s12, s12, s18
	s_addc_u32 s13, s13, s19
	s_add_i32 s28, s9, 2
	s_cmpk_gt_u32 s9, 0x8d
	v_pk_mul_f32 v[92:93], v[72:73], v[76:77]
	v_pk_mul_f32 v[76:77], v[84:85], v[90:91] op_sel_hi:[1,0]
	v_cvt_pk_bf16_f32 v72, v92, s0
	ds_write_b16 v139, v72 offset:4320
	v_mul_f32_e32 v72, v90, v104
	v_cvt_pk_bf16_f32 v72, v72, s0
	ds_write_b16 v139, v72 offset:2160
	v_cvt_pk_bf16_f32 v72, v93, s0
	ds_write_b16 v139, v72 offset:4464
	v_pk_mul_f32 v[72:73], v[74:75], v[90:91] op_sel_hi:[1,0]
	v_pk_mul_f32 v[74:75], v[78:79], v[90:91] op_sel_hi:[1,0]
	v_cvt_pk_bf16_f32 v72, v72, v73
	v_cvt_pk_bf16_f32 v73, v74, v75
	v_pk_mul_f32 v[74:75], v[82:83], v[90:91] op_sel_hi:[1,0]
	v_pk_mul_f32 v[78:79], v[80:81], v[90:91] op_sel_hi:[1,0]
	v_cvt_pk_bf16_f32 v74, v74, v75
	v_cvt_pk_bf16_f32 v75, v76, v77
	v_pk_mul_f32 v[76:77], v[86:87], v[90:91] op_sel_hi:[1,0]
	s_cselect_b64 s[50:51], -1, 0
	v_add_u32_e32 v207, v133, v132
	v_cvt_pk_bf16_f32 v76, v76, v77
	v_cvt_pk_bf16_f32 v77, v78, v79
	v_pk_mul_f32 v[78:79], v[88:89], v[90:91] op_sel_hi:[1,0]
	v_pk_mul_f32 v[80:81], v[92:93], v[90:91] op_sel_hi:[1,0]
	s_and_b64 vcc, exec, s[50:51]
	v_lshl_or_b32 v64, v152, 16, v153
	v_lshl_or_b32 v65, v160, 16, v161
	v_lshl_or_b32 v66, v169, 16, v159
	v_lshl_or_b32 v67, v167, 16, v168
	v_lshl_or_b32 v68, v176, 16, v177
	v_lshl_or_b32 v69, v192, 16, v193
	v_lshl_or_b32 v70, v210, 16, v191
	v_lshl_or_b32 v71, v199, 16, v209
	ds_write_b32 v207, v90 offset:8704
	v_cvt_pk_bf16_f32 v78, v78, v79
	v_cvt_pk_bf16_f32 v79, v80, v81
	ds_write_b128 v146, v[72:75] offset:4608
	ds_write_b128 v146, v[76:79] offset:4624
	ds_write_b128 v146, v[64:67] offset:6656
	ds_write_b128 v146, v[68:71] offset:6672
	s_add_u32 s100, s9, 2
	s_min_u32 s100, s100, 142
	s_lshl_b32 s12, s100, 4
	s_mov_b32 s18, 0x1600
	s_mov_b32 s19, 0
	s_cmp_eq_u64 s[38:39], 0
	s_cbranch_scc1 .Lhe_a1
	s_cmp_lt_u32 s100, 16
	s_movk_i32 s13, 0x9ff
	s_cselect_b32 s13, 0xff, s13
	s_sub_u32 s12, s13, s12
	s_mov_b32 s18, 0xffffea00
	s_mov_b32 s19, -1
; #define HM_LOAD(RQ, RZ, RV, j_) do { _Pragma("unroll") for (int i = 0; i < 16; ++i) { const bf16_t* pr_ = proj + HM_TOK((j_) * 16 + i) * INW; RQ[i] = pr_[qc]; RZ[i] = pr_[zc]; RV[i] = pr_[vc]; } } while (0)
; __device__ __forceinline__ void hgrn_mfma_unit(const Params& P, int l, LAS unsigned char* lds, int b, int half) {
;     ...
;             hm_stage(wl, aq, az, av, oml, lane);
;             if (j + 2 < NSC) HM_LOAD(aq, az, av, j + 2);
.Lhe_a1:
	s_add_u32 s12, s12, s64
	s_mul_i32 s12, s12, 0x1600
	s_add_u32 s12, s56, s12
	s_addc_u32 s13, s57, 0
	global_load_ushort v153, v130, s[12:13] offset:3072
	s_add_u32 s12, s12, s18
	s_addc_u32 s13, s13, s19
	global_load_ushort v152, v130, s[12:13] offset:3072
	s_add_u32 s12, s12, s18
	s_addc_u32 s13, s13, s19
	global_load_ushort v161, v130, s[12:13] offset:3072
	s_add_u32 s12, s12, s18
	s_addc_u32 s13, s13, s19
	global_load_ushort v160, v130, s[12:13] offset:3072
	s_add_u32 s12, s12, s18
	s_addc_u32 s13, s13, s19
	global_load_ushort v159, v130, s[12:13] offset:3072
	s_add_u32 s12, s12, s18
	s_addc_u32 s13, s13, s19
	global_load_ushort v169, v130, s[12:13] offset:3072
	s_add_u32 s12, s12, s18
	s_addc_u32 s13, s13, s19
	global_load_ushort v168, v130, s[12:13] offset:3072
	s_add_u32 s12, s12, s18
	s_addc_u32 s13, s13, s19
	global_load_ushort v167, v130, s[12:13] offset:3072
	s_add_u32 s12, s12, s18
	s_addc_u32 s13, s13, s19
	global_load_ushort v177, v130, s[12:13] offset:3072
	s_add_u32 s12, s12, s18
	s_addc_u32 s13, s13, s19
	global_load_ushort v176, v130, s[12:13] offset:3072
	s_add_u32 s12, s12, s18
	s_addc_u32 s13, s13, s19
	global_load_ushort v193, v130, s[12:13] offset:3072
	s_add_u32 s12, s12, s18
	s_addc_u32 s13, s13, s19
	global_load_ushort v192, v130, s[12:13] offset:3072
	s_add_u32 s12, s12, s18
	s_addc_u32 s13, s13, s19
	global_load_ushort v191, v130, s[12:13] offset:3072
	s_add_u32 s12, s12, s18
	s_addc_u32 s13, s13, s19
	global_load_ushort v210, v130, s[12:13] offset:3072
	s_add_u32 s12, s12, s18
	s_addc_u32 s13, s13, s19
	global_load_ushort v209, v130, s[12:13] offset:3072
	s_add_u32 s12, s12, s18
	s_addc_u32 s13, s13, s19
	global_load_ushort v199, v130, s[12:13] offset:3072

; #define LAS __attribute__((address_space(3)))
; __device__ __forceinline__ unsigned pk2(float lo, float hi) { f32x2_t v = {lo, hi}; bf16x2_t b = __builtin_convertvector(v, bf16x2_t); return __builtin_bit_cast(unsigned, b); }
; __device__ __forceinline__ float fast_exp2(float x) { return __builtin_amdgcn_exp2f(x); }
; #define HM_LOAD(RQ, RZ, RV, j_) do { _Pragma("unroll") for (int i = 0; i < 16; ++i) { const bf16_t* pr_ = proj + HM_TOK((j_) * 16 + i) * INW; RQ[i] = pr_[qc]; RZ[i] = pr_[zc]; RV[i] = pr_[vc]; } } while (0)
; #define HM_STORE_O(j_) do { float* op = odir + HM_TOK((j_) * 16 + c16) * 256 + h * 64 + 4 * g; _Pragma("unroll") for (int eb = 0; eb < 4; ++eb) *(f32x4*)(op + 16 * eb) = o[eb]; } while (0)
; __device__ __forceinline__ void hm_stage(LAS unsigned char* wl, const unsigned (&rq)[16], const unsigned (&rz)[16], const unsigned (&rv)[16], float oml, int lane) {
;     ...
;     for (int i = 0; i < 16; ++i) {
;         const float z = bf2f(rz[i]), q = bf2f(rq[i]);
;         const float sg = __builtin_amdgcn_rcpf(1.0f + fast_exp2(z * LOG2E));
;         const float k = oml * sg;
;         run = fmaxf(run * (1.0f - k), 8.673617379884035e-19f);
;         const float ieb = __builtin_amdgcn_rcpf(run);
;         kt[i] = k * ieb;
;         *(LAS unsigned short*)(wl + HM_QT + i * HM_QP + lane * 2) = (unsigned short)pk2(q * run, 0.f);
;         *(LAS unsigned short*)(wl + HM_KT + i * HM_QP + lane * 2) = (unsigned short)pk2(kt[i], 0.f);
;         if (i & 1) vpk[i >> 1] = rv[i - 1] | (rv[i] << 16);
;     }
; __device__ __forceinline__ void hgrn_mfma_unit(const Params& P, int l, LAS unsigned char* lds, int b, int half) {
;     ...
;         unsigned aq[16], az[16], av[16], bq[16], bz[16], bv[16];
;         HM_LOAD(aq, az, av, 0); HM_LOAD(bq, bz, bv, 1);
;         f32x4 S[4][4];
; #pragma unroll
;         for (int mb = 0; mb < 4; ++mb)
; #pragma unroll
;             for (int nb = 0; nb < 4; ++nb) S[mb][nb] = (f32x4){0.f, 0.f, 0.f, 0.f};
;         f32x4 o[4];
;         constexpr int NSC = TT / 16;
;         for (int j = 0; j < NSC; j += 2) {
;             hm_stage(wl, aq, az, av, oml, lane);
;             if (j + 2 < NSC) HM_LOAD(aq, az, av, j + 2);
;             hm_mfma(wl, S, o, c16, g);
;             HM_STORE_O(j);
;             hm_stage(wl, bq, bz, bv, oml, lane);
;             if (j + 3 < NSC) HM_LOAD(bq, bz, bv, j + 3);
.LBB0_584:
	s_or_b64 exec, exec, s[52:53]
	v_ashrrev_i32_e32 v5, 31, v4
	v_lshl_add_u64 v[4:5], v[4:5], 0, s[64:65]
	v_lshlrev_b64 v[4:5], 10, v[4:5]
	v_lshl_add_u64 v[4:5], v[140:141], 0, v[4:5]
	global_store_dwordx4 v[4:5], v[68:71], off
	global_store_dwordx4 v[4:5], v[72:75], off offset:64
	global_store_dwordx4 v[4:5], v[76:79], off offset:128
	global_store_dwordx4 v[4:5], v[80:83], off offset:192
	s_waitcnt vmcnt(52)
	s_add_u32 s100, s9, 3
	s_min_u32 s100, s100, 143
	s_lshl_b32 s12, s100, 4
	s_mov_b32 s18, 0x1600
	s_mov_b32 s19, 0
	s_cmp_eq_u64 s[38:39], 0
	s_cbranch_scc1 .Lhe_b0
	s_cmp_lt_u32 s100, 16
	s_movk_i32 s13, 0x9ff
	s_cselect_b32 s13, 0xff, s13
	s_sub_u32 s12, s13, s12
	s_mov_b32 s18, 0xffffea00
	s_mov_b32 s19, -1
.Lhe_b0:
	s_add_u32 s12, s12, s64
	s_mul_i32 s12, s12, 0x1600
	s_add_u32 s12, s56, s12
	s_addc_u32 s13, s57, 0
	v_lshlrev_b32_e32 v4, 16, v216
	v_mul_f32_e32 v4, 0x3fb8aa3b, v4
	v_exp_f32_e32 v4, v4
	v_lshlrev_b32_e32 v89, 16, v214
	global_load_ushort v214, v130, s[12:13] offset:1536
	global_load_ushort v216, v134, s[12:13]
	s_add_u32 s12, s12, s18
	s_addc_u32 s13, s13, s19
	v_lshlrev_b32_e32 v90, 16, v213
	v_lshlrev_b32_e32 v91, 16, v212
	v_add_f32_e32 v4, 1.0, v4
	v_rcp_f32_e32 v10, v4
	v_lshlrev_b32_e32 v4, 16, v215
	global_load_ushort v213, v130, s[12:13] offset:1536
	global_load_ushort v215, v134, s[12:13]
	s_add_u32 s12, s12, s18
	s_addc_u32 s13, s13, s19
	v_mul_f32_e32 v4, 0x3fb8aa3b, v4
	v_exp_f32_e32 v4, v4
	v_lshlrev_b32_e32 v92, 16, v220
	v_lshlrev_b32_e32 v93, 16, v219
	v_lshlrev_b32_e32 v94, 16, v229
	v_add_f32_e32 v4, 1.0, v4
	v_rcp_f32_e32 v11, v4
	v_lshlrev_b32_e32 v4, 16, v224
	global_load_ushort v212, v130, s[12:13] offset:1536
	global_load_ushort v224, v134, s[12:13]
	s_add_u32 s12, s12, s18
	s_addc_u32 s13, s13, s19
	v_mul_f32_e32 v4, 0x3fb8aa3b, v4
	v_exp_f32_e32 v4, v4
	v_pk_mul_f32 v[10:11], v[136:137], v[10:11]
	v_lshlrev_b32_e32 v95, 16, v228
	v_sub_f32_e32 v88, 1.0, v10
	v_max_f32_e32 v119, 0x21800000, v88
	v_add_f32_e32 v4, 1.0, v4
	v_mul_f32_e32 v89, v119, v89
	v_rcp_f32_e32 v78, v4
	v_lshlrev_b32_e32 v4, 16, v222
	global_load_ushort v220, v130, s[12:13] offset:1536
	global_load_ushort v222, v134, s[12:13]
	s_add_u32 s12, s12, s18
	s_addc_u32 s13, s13, s19
	v_cvt_pk_bf16_f32 v89, v89, s0
	v_mul_f32_e32 v4, 0x3fb8aa3b, v4
	ds_write_b16 v139, v89
	v_sub_f32_e32 v89, 1.0, v11
	v_exp_f32_e32 v4, v4
	v_mul_f32_e32 v89, v89, v119
	v_rcp_f32_e32 v88, v119
	v_max_f32_e32 v119, 0x21800000, v89
	v_rcp_f32_e32 v89, v119
	v_add_f32_e32 v4, 1.0, v4
	v_rcp_f32_e32 v79, v4
	v_lshlrev_b32_e32 v4, 16, v221
	global_load_ushort v219, v130, s[12:13] offset:1536
	global_load_ushort v221, v134, s[12:13]
	s_add_u32 s12, s12, s18
	s_addc_u32 s13, s13, s19
	v_mul_f32_e32 v4, 0x3fb8aa3b, v4
	v_pk_mul_f32 v[10:11], v[10:11], v[88:89]
	v_exp_f32_e32 v4, v4
	v_cvt_pk_bf16_f32 v88, v10, s0
	ds_write_b16 v139, v88 offset:2304
	v_mul_f32_e32 v88, v119, v90
	v_pk_mul_f32 v[78:79], v[136:137], v[78:79]
	v_cvt_pk_bf16_f32 v88, v88, s0
	v_sub_f32_e32 v117, 1.0, v78
	ds_write_b16 v139, v88 offset:144
	v_cvt_pk_bf16_f32 v88, v11, s0
	v_add_f32_e32 v4, 1.0, v4
	ds_write_b16 v139, v88 offset:2448
	v_mul_f32_e32 v88, v117, v119
	v_rcp_f32_e32 v82, v4
	v_lshlrev_b32_e32 v4, 16, v231
	global_load_ushort v229, v130, s[12:13] offset:1536
	global_load_ushort v231, v134, s[12:13]
	s_add_u32 s12, s12, s18
	s_addc_u32 s13, s13, s19
	v_max_f32_e32 v89, 0x21800000, v88
	v_mul_f32_e32 v4, 0x3fb8aa3b, v4
	v_sub_f32_e32 v118, 1.0, v79
	v_mul_f32_e32 v90, v89, v91
	v_exp_f32_e32 v4, v4
	v_rcp_f32_e32 v88, v89
	v_cvt_pk_bf16_f32 v90, v90, s0
	v_mul_f32_e32 v89, v118, v89
	ds_write_b16 v139, v90 offset:288
	v_max_f32_e32 v90, 0x21800000, v89
	v_rcp_f32_e32 v89, v90
	v_add_f32_e32 v4, 1.0, v4
	v_rcp_f32_e32 v83, v4
	v_lshlrev_b32_e32 v4, 16, v230
	global_load_ushort v228, v130, s[12:13] offset:1536
	global_load_ushort v230, v134, s[12:13]
	s_add_u32 s12, s12, s18
	s_addc_u32 s13, s13, s19
	v_mul_f32_e32 v4, 0x3fb8aa3b, v4
	v_pk_mul_f32 v[78:79], v[78:79], v[88:89]
	v_exp_f32_e32 v4, v4
	v_cvt_pk_bf16_f32 v88, v78, s0
	ds_write_b16 v139, v88 offset:2592
	v_mul_f32_e32 v88, v90, v92
	v_pk_mul_f32 v[82:83], v[136:137], v[82:83]
	v_cvt_pk_bf16_f32 v88, v88, s0
	v_sub_f32_e32 v115, 1.0, v82
	ds_write_b16 v139, v88 offset:432
	v_cvt_pk_bf16_f32 v88, v79, s0
	v_add_f32_e32 v4, 1.0, v4
	ds_write_b16 v139, v88 offset:2736
	v_mul_f32_e32 v88, v115, v90
	v_rcp_f32_e32 v84, v4
	v_lshlrev_b32_e32 v4, 16, v240
	v_max_f32_e32 v89, 0x21800000, v88
	v_mul_f32_e32 v4, 0x3fb8aa3b, v4
	v_sub_f32_e32 v116, 1.0, v83
	v_mul_f32_e32 v90, v89, v93
	v_exp_f32_e32 v4, v4
	v_rcp_f32_e32 v88, v89
	v_cvt_pk_bf16_f32 v90, v90, s0
	v_mul_f32_e32 v89, v116, v89
	ds_write_b16 v139, v90 offset:576
	v_max_f32_e32 v90, 0x21800000, v89
	v_rcp_f32_e32 v89, v90
	v_add_f32_e32 v4, 1.0, v4
	v_rcp_f32_e32 v85, v4
	v_lshlrev_b32_e32 v4, 16, v239
	v_mul_f32_e32 v4, 0x3fb8aa3b, v4
	v_pk_mul_f32 v[82:83], v[82:83], v[88:89]
	v_exp_f32_e32 v4, v4
	v_cvt_pk_bf16_f32 v88, v82, s0
	ds_write_b16 v139, v88 offset:2880
	v_mul_f32_e32 v88, v90, v94
	v_pk_mul_f32 v[84:85], v[136:137], v[84:85]
	v_cvt_pk_bf16_f32 v88, v88, s0
	v_sub_f32_e32 v113, 1.0, v84
	ds_write_b16 v139, v88 offset:720
	v_cvt_pk_bf16_f32 v88, v83, s0
	v_add_f32_e32 v4, 1.0, v4
	ds_write_b16 v139, v88 offset:3024
	v_mul_f32_e32 v88, v113, v90
	v_rcp_f32_e32 v86, v4
	v_lshlrev_b32_e32 v4, 16, v238
	v_max_f32_e32 v89, 0x21800000, v88
	v_mul_f32_e32 v4, 0x3fb8aa3b, v4
	v_sub_f32_e32 v114, 1.0, v85
	v_mul_f32_e32 v90, v89, v95
	v_exp_f32_e32 v4, v4
	v_rcp_f32_e32 v88, v89
	v_cvt_pk_bf16_f32 v90, v90, s0
	v_mul_f32_e32 v89, v114, v89
; #define LAS __attribute__((address_space(3)))
; __device__ __forceinline__ unsigned pk2(float lo, float hi) { f32x2_t v = {lo, hi}; bf16x2_t b = __builtin_convertvector(v, bf16x2_t); return __builtin_bit_cast(unsigned, b); }
; __device__ __forceinline__ float fast_exp2(float x) { return __builtin_amdgcn_exp2f(x); }
; #define HM_LOAD(RQ, RZ, RV, j_) do { _Pragma("unroll") for (int i = 0; i < 16; ++i) { const bf16_t* pr_ = proj + HM_TOK((j_) * 16 + i) * INW; RQ[i] = pr_[qc]; RZ[i] = pr_[zc]; RV[i] = pr_[vc]; } } while (0)
; __device__ __forceinline__ void hm_stage(LAS unsigned char* wl, const unsigned (&rq)[16], const unsigned (&rz)[16], const unsigned (&rv)[16], float oml, int lane) {
;     ...
;     for (int i = 0; i < 16; ++i) {
;         const float z = bf2f(rz[i]), q = bf2f(rq[i]);
;         const float sg = __builtin_amdgcn_rcpf(1.0f + fast_exp2(z * LOG2E));
;         const float k = oml * sg;
;         run = fmaxf(run * (1.0f - k), 8.673617379884035e-19f);
;         const float ieb = __builtin_amdgcn_rcpf(run);
;         kt[i] = k * ieb;
;         *(LAS unsigned short*)(wl + HM_QT + i * HM_QP + lane * 2) = (unsigned short)pk2(q * run, 0.f);
;         *(LAS unsigned short*)(wl + HM_KT + i * HM_QP + lane * 2) = (unsigned short)pk2(kt[i], 0.f);
;         if (i & 1) vpk[i >> 1] = rv[i - 1] | (rv[i] << 16);
;     }
;     const float eB = run;
;     *(LAS float*)(wl + HM_EB + lane * 4) = eB;
;     u32x4 w0, w1;
;     w0.x = pk2(kt[0] * eB, kt[1] * eB); w0.y = pk2(kt[2] * eB, kt[3] * eB); w0.z = pk2(kt[4] * eB, kt[5] * eB); w0.w = pk2(kt[6] * eB, kt[7] * eB);
;     w1.x = pk2(kt[8] * eB, kt[9] * eB); w1.y = pk2(kt[10] * eB, kt[11] * eB); w1.z = pk2(kt[12] * eB, kt[13] * eB); w1.w = pk2(kt[14] * eB, kt[15] * eB);
;     *(LAS u32x4*)(wl + HM_KD + lane * 32) = w0; *(LAS u32x4*)(wl + HM_KD + lane * 32 + 16) = w1;
;     *(LAS u32x4*)(wl + HM_VT + lane * 32) = (u32x4){vpk[0], vpk[1], vpk[2], vpk[3]}; *(LAS u32x4*)(wl + HM_VT + lane * 32 + 16) = (u32x4){vpk[4], vpk[5], vpk[6], vpk[7]};
; __device__ __forceinline__ void hgrn_mfma_unit(const Params& P, int l, LAS unsigned char* lds, int b, int half) {
;     ...
;             hm_stage(wl, bq, bz, bv, oml, lane);
;             if (j + 3 < NSC) HM_LOAD(bq, bz, bv, j + 3);
	ds_write_b16 v139, v90 offset:864
	v_max_f32_e32 v90, 0x21800000, v89
	v_rcp_f32_e32 v89, v90
	v_add_f32_e32 v4, 1.0, v4
	v_rcp_f32_e32 v87, v4
	v_lshlrev_b32_e32 v4, 16, v248
	v_mul_f32_e32 v4, 0x3fb8aa3b, v4
	v_pk_mul_f32 v[84:85], v[84:85], v[88:89]
	v_lshlrev_b32_e32 v96, 16, v227
	global_load_ushort v227, v130, s[12:13] offset:1536
	global_load_ushort v240, v134, s[12:13]
	s_add_u32 s12, s12, s18
	s_addc_u32 s13, s13, s19
	v_exp_f32_e32 v4, v4
	v_cvt_pk_bf16_f32 v88, v84, s0
	ds_write_b16 v139, v88 offset:3168
	v_mul_f32_e32 v88, v90, v96
	v_pk_mul_f32 v[86:87], v[136:137], v[86:87]
	v_cvt_pk_bf16_f32 v88, v88, s0
	v_sub_f32_e32 v111, 1.0, v86
	ds_write_b16 v139, v88 offset:1008
	v_cvt_pk_bf16_f32 v88, v85, s0
	v_add_f32_e32 v4, 1.0, v4
	ds_write_b16 v139, v88 offset:3312
	v_mul_f32_e32 v88, v111, v90
	v_lshlrev_b32_e32 v97, 16, v237
	global_load_ushort v237, v130, s[12:13] offset:1536
	global_load_ushort v239, v134, s[12:13]
	s_add_u32 s12, s12, s18
	s_addc_u32 s13, s13, s19
	v_rcp_f32_e32 v80, v4
	v_lshlrev_b32_e32 v4, 16, v246
	v_max_f32_e32 v89, 0x21800000, v88
	v_mul_f32_e32 v4, 0x3fb8aa3b, v4
	v_sub_f32_e32 v112, 1.0, v87
	v_mul_f32_e32 v90, v89, v97
	v_exp_f32_e32 v4, v4
	v_rcp_f32_e32 v88, v89
	v_cvt_pk_bf16_f32 v90, v90, s0
	v_mul_f32_e32 v89, v112, v89
	ds_write_b16 v139, v90 offset:1152
	v_max_f32_e32 v90, 0x21800000, v89
	v_rcp_f32_e32 v89, v90
	v_add_f32_e32 v4, 1.0, v4
	v_rcp_f32_e32 v81, v4
	v_lshlrev_b32_e32 v4, 16, v245
	v_mul_f32_e32 v4, 0x3fb8aa3b, v4
	v_pk_mul_f32 v[86:87], v[86:87], v[88:89]
	v_lshlrev_b32_e32 v98, 16, v236
	global_load_ushort v236, v130, s[12:13] offset:1536
	global_load_ushort v238, v134, s[12:13]
	s_add_u32 s12, s12, s18
	s_addc_u32 s13, s13, s19
	v_exp_f32_e32 v4, v4
	v_cvt_pk_bf16_f32 v88, v86, s0
	ds_write_b16 v139, v88 offset:3456
	v_mul_f32_e32 v88, v90, v98
	v_pk_mul_f32 v[80:81], v[136:137], v[80:81]
	v_cvt_pk_bf16_f32 v88, v88, s0
	v_sub_f32_e32 v109, 1.0, v80
	ds_write_b16 v139, v88 offset:1296
	v_cvt_pk_bf16_f32 v88, v87, s0
	v_add_f32_e32 v4, 1.0, v4
	ds_write_b16 v139, v88 offset:3600
	v_mul_f32_e32 v88, v109, v90
	v_lshlrev_b32_e32 v99, 16, v235
	global_load_ushort v235, v130, s[12:13] offset:1536
	global_load_ushort v248, v134, s[12:13]
	s_add_u32 s12, s12, s18
	s_addc_u32 s13, s13, s19
	v_rcp_f32_e32 v76, v4
	v_lshlrev_b32_e32 v4, 16, v206
	v_max_f32_e32 v89, 0x21800000, v88
	v_mul_f32_e32 v4, 0x3fb8aa3b, v4
	v_sub_f32_e32 v110, 1.0, v81
	v_mul_f32_e32 v90, v89, v99
	v_exp_f32_e32 v4, v4
	v_rcp_f32_e32 v88, v89
	v_cvt_pk_bf16_f32 v90, v90, s0
	v_mul_f32_e32 v89, v110, v89
	ds_write_b16 v139, v90 offset:1440
	v_max_f32_e32 v90, 0x21800000, v89
	v_rcp_f32_e32 v89, v90
	v_add_f32_e32 v4, 1.0, v4
	v_rcp_f32_e32 v77, v4
	v_lshlrev_b32_e32 v100, 16, v244
	global_load_ushort v244, v130, s[12:13] offset:1536
	global_load_ushort v246, v134, s[12:13]
	s_add_u32 s12, s12, s18
	s_addc_u32 s13, s13, s19
	v_pk_mul_f32 v[88:89], v[80:81], v[88:89]
	v_lshlrev_b32_e32 v4, 16, v204
	v_cvt_pk_bf16_f32 v80, v88, s0
	ds_write_b16 v139, v80 offset:3744
	v_mul_f32_e32 v80, v90, v100
	v_pk_mul_f32 v[76:77], v[136:137], v[76:77]
	v_cvt_pk_bf16_f32 v80, v80, s0
	v_sub_f32_e32 v107, 1.0, v76
	ds_write_b16 v139, v80 offset:1584
	v_cvt_pk_bf16_f32 v80, v89, s0
	v_lshlrev_b32_e32 v5, 16, v178
	ds_write_b16 v139, v80 offset:3888
	v_mul_f32_e32 v80, v107, v90
	v_lshlrev_b32_e32 v101, 16, v243
	global_load_ushort v243, v130, s[12:13] offset:1536
	global_load_ushort v245, v134, s[12:13]
	s_add_u32 s12, s12, s18
	s_addc_u32 s13, s13, s19
	v_mul_f32_e32 v4, 0x3fb8aa3b, v4
	v_mul_f32_e32 v5, 0x3fb8aa3b, v5
	v_sub_f32_e32 v108, 1.0, v77
	v_max_f32_e32 v81, 0x21800000, v80
	v_exp_f32_e32 v4, v4
	v_exp_f32_e32 v5, v5
	v_rcp_f32_e32 v80, v81
	v_mul_f32_e32 v90, v81, v101
	v_mul_f32_e32 v81, v108, v81
	v_max_f32_e32 v92, 0x21800000, v81
	v_rcp_f32_e32 v81, v92
	v_add_f32_e32 v4, 1.0, v4
	v_add_f32_e32 v5, 1.0, v5
	v_rcp_f32_e32 v4, v4
	v_rcp_f32_e32 v5, v5
	v_cvt_pk_bf16_f32 v90, v90, s0
	ds_write_b16 v139, v90 offset:1728
	v_pk_mul_f32 v[90:91], v[76:77], v[80:81]
	v_lshlrev_b32_e32 v102, 16, v205
	global_load_ushort v205, v130, s[12:13] offset:1536
	global_load_ushort v206, v134, s[12:13]
	s_add_u32 s12, s12, s18
	s_addc_u32 s13, s13, s19
	v_cvt_pk_bf16_f32 v76, v90, s0
	ds_write_b16 v139, v76 offset:4032
	v_mul_f32_e32 v76, v92, v102
	v_pk_mul_f32 v[4:5], v[136:137], v[4:5]
	v_cvt_pk_bf16_f32 v76, v76, s0
	v_sub_f32_e32 v105, 1.0, v4
	ds_write_b16 v139, v76 offset:1872
	v_cvt_pk_bf16_f32 v76, v91, s0
	ds_write_b16 v139, v76 offset:4176
	v_mul_f32_e32 v76, v105, v92
	v_lshlrev_b32_e32 v103, 16, v252
	global_load_ushort v252, v130, s[12:13] offset:1536
	global_load_ushort v204, v134, s[12:13]
	s_add_u32 s12, s12, s18
	s_addc_u32 s13, s13, s19
	v_sub_f32_e32 v106, 1.0, v5
	v_max_f32_e32 v77, 0x21800000, v76
	v_rcp_f32_e32 v76, v77
	v_mul_f32_e32 v80, v77, v103
	v_mul_f32_e32 v77, v106, v77
	v_max_f32_e32 v92, 0x21800000, v77
	v_rcp_f32_e32 v77, v92
	v_lshlrev_b32_e32 v104, 16, v251
	global_load_ushort v251, v130, s[12:13] offset:1536
	global_load_ushort v178, v134, s[12:13]
	s_add_u32 s12, s12, s18
	s_addc_u32 s13, s13, s19
	v_cvt_pk_bf16_f32 v80, v80, s0
	v_pk_mul_f32 v[10:11], v[10:11], v[92:93] op_sel_hi:[1,0]
	v_pk_mul_f32 v[4:5], v[4:5], v[76:77]
	ds_write_b16 v139, v80 offset:2016
	v_cvt_pk_bf16_f32 v76, v4, s0
	ds_write_b16 v139, v76 offset:4320
	v_mul_f32_e32 v76, v92, v104
	v_cvt_pk_bf16_f32 v76, v76, s0
	ds_write_b16 v139, v76 offset:2160
	v_cvt_pk_bf16_f32 v76, v5, s0
	ds_write_b16 v139, v76 offset:4464
	ds_write_b32 v207, v92 offset:8704
	v_cvt_pk_bf16_f32 v76, v10, v11
	v_pk_mul_f32 v[10:11], v[78:79], v[92:93] op_sel_hi:[1,0]
	v_pk_mul_f32 v[4:5], v[4:5], v[92:93] op_sel_hi:[1,0]
	v_cvt_pk_bf16_f32 v77, v10, v11
	v_pk_mul_f32 v[10:11], v[82:83], v[92:93] op_sel_hi:[1,0]
	s_cmpk_gt_u32 s9, 0x8c
	v_cvt_pk_bf16_f32 v78, v10, v11
	v_pk_mul_f32 v[10:11], v[84:85], v[92:93] op_sel_hi:[1,0]
	v_lshl_or_b32 v68, v217, 16, v218
	v_cvt_pk_bf16_f32 v79, v10, v11
	v_pk_mul_f32 v[10:11], v[86:87], v[92:93] op_sel_hi:[1,0]
	v_lshl_or_b32 v69, v225, 16, v226
	v_cvt_pk_bf16_f32 v80, v10, v11
	v_pk_mul_f32 v[10:11], v[88:89], v[92:93] op_sel_hi:[1,0]
	v_lshl_or_b32 v70, v234, 16, v223
	v_cvt_pk_bf16_f32 v81, v10, v11
	v_pk_mul_f32 v[10:11], v[90:91], v[92:93] op_sel_hi:[1,0]
	v_lshl_or_b32 v71, v232, 16, v233
	v_lshl_or_b32 v72, v241, 16, v242
	v_lshl_or_b32 v73, v249, 16, v250
	v_lshl_or_b32 v74, v180, 16, v247
	v_lshl_or_b32 v75, v208, 16, v179
	v_cvt_pk_bf16_f32 v82, v10, v11
	v_cvt_pk_bf16_f32 v83, v4, v5
	ds_write_b128 v146, v[76:79] offset:4608
	ds_write_b128 v146, v[80:83] offset:4624
	ds_write_b128 v146, v[68:71] offset:6656
	ds_write_b128 v146, v[72:75] offset:6672
	s_add_u32 s100, s9, 3
	s_min_u32 s100, s100, 143
	s_lshl_b32 s12, s100, 4
	s_mov_b32 s18, 0x1600
	s_mov_b32 s19, 0
	s_cmp_eq_u64 s[38:39], 0
	s_cbranch_scc1 .Lhe_b1
	s_cmp_lt_u32 s100, 16
	s_movk_i32 s13, 0x9ff
	s_cselect_b32 s13, 0xff, s13
	s_sub_u32 s12, s13, s12
	s_mov_b32 s18, 0xffffea00
	s_mov_b32 s19, -1
; #define HM_LOAD(RQ, RZ, RV, j_) do { _Pragma("unroll") for (int i = 0; i < 16; ++i) { const bf16_t* pr_ = proj + HM_TOK((j_) * 16 + i) * INW; RQ[i] = pr_[qc]; RZ[i] = pr_[zc]; RV[i] = pr_[vc]; } } while (0)
; __device__ __forceinline__ void hgrn_mfma_unit(const Params& P, int l, LAS unsigned char* lds, int b, int half) {
;     ...
;             hm_stage(wl, bq, bz, bv, oml, lane);
;             if (j + 3 < NSC) HM_LOAD(bq, bz, bv, j + 3);
.Lhe_b1:
	s_add_u32 s12, s12, s64
	s_mul_i32 s12, s12, 0x1600
	s_add_u32 s12, s56, s12
	s_addc_u32 s13, s57, 0
	global_load_ushort v218, v130, s[12:13] offset:3072
	s_add_u32 s12, s12, s18
	s_addc_u32 s13, s13, s19
	global_load_ushort v217, v130, s[12:13] offset:3072
	s_add_u32 s12, s12, s18
	s_addc_u32 s13, s13, s19
	global_load_ushort v226, v130, s[12:13] offset:3072
	s_add_u32 s12, s12, s18
	s_addc_u32 s13, s13, s19
	global_load_ushort v225, v130, s[12:13] offset:3072
	s_add_u32 s12, s12, s18
	s_addc_u32 s13, s13, s19
	global_load_ushort v223, v130, s[12:13] offset:3072
	s_add_u32 s12, s12, s18
	s_addc_u32 s13, s13, s19
	global_load_ushort v234, v130, s[12:13] offset:3072
	s_add_u32 s12, s12, s18
	s_addc_u32 s13, s13, s19
	global_load_ushort v233, v130, s[12:13] offset:3072
	s_add_u32 s12, s12, s18
	s_addc_u32 s13, s13, s19
	global_load_ushort v232, v130, s[12:13] offset:3072
	s_add_u32 s12, s12, s18
	s_addc_u32 s13, s13, s19
	global_load_ushort v242, v130, s[12:13] offset:3072
	s_add_u32 s12, s12, s18
	s_addc_u32 s13, s13, s19
	global_load_ushort v241, v130, s[12:13] offset:3072
	s_add_u32 s12, s12, s18
	s_addc_u32 s13, s13, s19
	global_load_ushort v250, v130, s[12:13] offset:3072
	s_add_u32 s12, s12, s18
	s_addc_u32 s13, s13, s19
	global_load_ushort v249, v130, s[12:13] offset:3072
	s_add_u32 s12, s12, s18
	s_addc_u32 s13, s13, s19
	global_load_ushort v247, v130, s[12:13] offset:3072
	s_add_u32 s12, s12, s18
	s_addc_u32 s13, s13, s19
	global_load_ushort v180, v130, s[12:13] offset:3072
	s_add_u32 s12, s12, s18
	s_addc_u32 s13, s13, s19
	global_load_ushort v179, v130, s[12:13] offset:3072
	s_add_u32 s12, s12, s18
	s_addc_u32 s13, s13, s19
	global_load_ushort v208, v130, s[12:13] offset:3072

; __device__ __forceinline__ void hgrn_mfma_unit(const Params& P, int l, LAS unsigned char* lds, int b, int half) {
;     ...
;     }
;     __syncthreads();
; }
.LBB0_718:
	s_waitcnt vmcnt(0)
	s_or_b64 exec, exec, s[10:11]
	v_mov_b32_e32 v242, v203
	v_mov_b32_e32 v203, v201
	v_mov_b32_e32 v201, v202
	v_mov_b32_e32 v202, 0x260
	s_barrier
